# MLA latent epilogue gate prefetch issued at the start of the item's last softmax stage (hidden under the final P.V stage) instead of at the epilogue head
# baseline (speedup 1.0000x reference)
.LBB0_502:
	s_or_b64 exec, exec, s[16:17]
	v_add_f32_e32 v64, v64, v65
	v_fmac_f32_e32 v64, v186, v96
	v_rcp_f32_e32 v67, v64
	s_lshl_b64 s[14:15], s[14:15], 12
	s_add_u32 s14, s23, s14
	s_addc_u32 s15, s24, s15
	v_mul_f32_e32 v16, v67, v16
	v_mul_f32_e32 v17, v67, v17
	v_cvt_pk_bf16_f32 v80, v16, v17
	v_mul_f32_e32 v16, v67, v18
	v_mul_f32_e32 v17, v67, v19
	v_cvt_pk_bf16_f32 v81, v16, v17
	v_mul_f32_e32 v16, v67, v20
	v_mul_f32_e32 v17, v67, v21
	v_cvt_pk_bf16_f32 v82, v16, v17
	v_mul_f32_e32 v16, v67, v22
	v_mul_f32_e32 v17, v67, v23
	v_cvt_pk_bf16_f32 v83, v16, v17
	v_mul_f32_e32 v16, v67, v24
	v_mul_f32_e32 v17, v67, v25
	v_cvt_pk_bf16_f32 v84, v16, v17
	v_mul_f32_e32 v16, v67, v26
	v_mul_f32_e32 v17, v67, v27
	v_cvt_pk_bf16_f32 v85, v16, v17
	v_mul_f32_e32 v16, v67, v28
	v_mul_f32_e32 v17, v67, v29
	v_cvt_pk_bf16_f32 v86, v16, v17
	v_mul_f32_e32 v16, v67, v30
	v_mul_f32_e32 v17, v67, v31
	v_cvt_pk_bf16_f32 v87, v16, v17
	v_mul_f32_e32 v16, v67, v32
	v_mul_f32_e32 v17, v67, v33
	v_cvt_pk_bf16_f32 v88, v16, v17
	v_mul_f32_e32 v16, v67, v34
	v_mul_f32_e32 v17, v67, v35
	v_cvt_pk_bf16_f32 v89, v16, v17
	v_mul_f32_e32 v16, v67, v36
	v_mul_f32_e32 v17, v67, v37
	v_cvt_pk_bf16_f32 v90, v16, v17
	v_mul_f32_e32 v16, v67, v38
	v_mul_f32_e32 v17, v67, v39
	v_cvt_pk_bf16_f32 v91, v16, v17
	v_mul_f32_e32 v16, v67, v40
	v_mul_f32_e32 v17, v67, v41
	v_cvt_pk_bf16_f32 v92, v16, v17
	v_mul_f32_e32 v16, v67, v42
	v_mul_f32_e32 v17, v67, v43
	v_cvt_pk_bf16_f32 v93, v16, v17
	v_mul_f32_e32 v16, v67, v44
	v_mul_f32_e32 v17, v67, v45
	v_cvt_pk_bf16_f32 v94, v16, v17
	v_mul_f32_e32 v16, v67, v46
	v_mul_f32_e32 v17, v67, v47
	v_cvt_pk_bf16_f32 v95, v16, v17
	v_mul_f32_e32 v16, v67, v48
	v_mul_f32_e32 v17, v67, v49
	v_cvt_pk_bf16_f32 v76, v16, v17
	v_mul_f32_e32 v16, v67, v50
	v_mul_f32_e32 v17, v67, v51
	v_cvt_pk_bf16_f32 v77, v16, v17
	v_mul_f32_e32 v16, v67, v52
	v_mul_f32_e32 v17, v67, v53
	v_cvt_pk_bf16_f32 v78, v16, v17
	v_mul_f32_e32 v16, v67, v54
	v_mul_f32_e32 v17, v67, v55
	v_cvt_pk_bf16_f32 v79, v16, v17
	v_mul_f32_e32 v16, v67, v56
	v_mul_f32_e32 v17, v67, v57
	v_cvt_pk_bf16_f32 v72, v16, v17
	v_mul_f32_e32 v16, v67, v58
	v_mul_f32_e32 v17, v67, v59
	v_cvt_pk_bf16_f32 v73, v16, v17
	v_mul_f32_e32 v16, v67, v60
	v_mul_f32_e32 v17, v67, v61
	v_mul_f32_e32 v0, v67, v0
	v_mul_f32_e32 v1, v67, v1
	v_cvt_pk_bf16_f32 v74, v16, v17
	v_mul_f32_e32 v16, v67, v62
	v_mul_f32_e32 v17, v67, v63
	v_cvt_pk_bf16_f32 v75, v16, v17
	v_cvt_pk_bf16_f32 v68, v0, v1
	v_mul_f32_e32 v0, v67, v2
	v_mul_f32_e32 v1, v67, v3
	v_cvt_pk_bf16_f32 v69, v0, v1
	v_mul_f32_e32 v0, v67, v4
	v_mul_f32_e32 v1, v67, v5
	v_cvt_pk_bf16_f32 v70, v0, v1
	v_mul_f32_e32 v0, v67, v6
	v_mul_f32_e32 v1, v67, v7
	s_lshl_b32 s16, s0, 8
	v_cvt_pk_bf16_f32 v71, v0, v1
	v_mul_f32_e32 v0, v67, v8
	v_mul_f32_e32 v1, v67, v9
	s_add_u32 s14, s14, s16
	v_cvt_pk_bf16_f32 v64, v0, v1
	v_mul_f32_e32 v0, v67, v10
	v_mul_f32_e32 v1, v67, v11
	s_addc_u32 s15, s15, 0
	v_cvt_pk_bf16_f32 v65, v0, v1
	v_mul_f32_e32 v0, v67, v12
	v_mul_f32_e32 v1, v67, v13
	s_lshl_b32 s0, s0, 15
	v_cvt_pk_bf16_f32 v66, v0, v1
	v_mul_f32_e32 v0, v67, v14
	v_mul_f32_e32 v1, v67, v15
	v_lshl_add_u64 v[62:63], v[152:153], 0, s[0:1]
	v_cvt_pk_bf16_f32 v67, v0, v1
	global_load_dwordx2 v[0:1], v[62:63], off
	global_load_dwordx2 v[2:3], v[62:63], off offset:16
	global_load_dwordx2 v[16:17], v[62:63], off offset:32
	global_load_dwordx2 v[18:19], v[62:63], off offset:48
	global_load_dwordx2 v[20:21], v[62:63], off offset:64
	global_load_dwordx2 v[22:23], v[62:63], off offset:80
	global_load_dwordx2 v[24:25], v[62:63], off offset:96
	global_load_dwordx2 v[26:27], v[62:63], off offset:112
	global_load_dwordx2 v[28:29], v[62:63], off offset:128
	global_load_dwordx2 v[30:31], v[62:63], off offset:144
	v_add_co_u32_e32 v48, vcc, s36, v62
	s_waitcnt vmcnt(0)
	v_mfma_f32_32x32x16_bf16 v[0:15], v[0:3], v[80:83], 0
	v_addc_co_u32_e32 v49, vcc, 0, v63, vcc
	v_add_co_u32_e32 v138, vcc, s37, v62
	s_add_i32 s41, s41, s60
	s_nop 0
	v_addc_co_u32_e32 v139, vcc, 0, v63, vcc
	v_mfma_f32_32x32x16_bf16 v[0:15], v[16:19], v[84:87], v[0:15]
	global_load_dwordx2 v[16:17], v[62:63], off offset:160
	global_load_dwordx2 v[18:19], v[62:63], off offset:176
	v_add_co_u32_e32 v146, vcc, s40, v62
	s_cmpk_gt_i32 s41, 0x7ff
	s_nop 0
	v_addc_co_u32_e32 v147, vcc, 0, v63, vcc
	v_mfma_f32_32x32x16_bf16 v[0:15], v[20:23], v[88:91], v[0:15]
	global_load_dwordx2 v[20:21], v[62:63], off offset:192
	global_load_dwordx2 v[22:23], v[62:63], off offset:208
	v_mfma_f32_32x32x16_bf16 v[0:15], v[24:27], v[92:95], v[0:15]
	global_load_dwordx2 v[24:25], v[48:49], off
	global_load_dwordx2 v[26:27], v[48:49], off offset:16
	global_load_dwordx2 v[32:33], v[62:63], off offset:224
	global_load_dwordx2 v[34:35], v[62:63], off offset:240
	global_load_dwordx2 v[36:37], v[48:49], off offset:32
	global_load_dwordx2 v[38:39], v[48:49], off offset:48
	global_load_dwordx2 v[40:41], v[48:49], off offset:64
	global_load_dwordx2 v[42:43], v[48:49], off offset:80
	global_load_dwordx2 v[44:45], v[48:49], off offset:96
	global_load_dwordx2 v[46:47], v[48:49], off offset:112
	v_lshl_add_u64 v[62:63], s[14:15], 0, v[154:155]
	v_lshl_add_u64 v[96:97], v[62:63], 0, v[150:151]
	v_mfma_f32_32x32x16_bf16 v[0:15], v[28:31], v[76:79], v[0:15]
	s_waitcnt vmcnt(0)
	v_mfma_f32_32x32x16_bf16 v[0:15], v[16:19], v[72:75], v[0:15]
	v_mfma_f32_32x32x16_bf16 v[0:15], v[20:23], v[68:71], v[0:15]
	v_mfma_f32_32x32x16_bf16 v[0:15], v[32:35], v[64:67], v[0:15]
	global_load_dwordx2 v[32:33], v[138:139], off
	global_load_dwordx2 v[34:35], v[138:139], off offset:16
	global_load_dwordx2 v[50:51], v[138:139], off offset:32
	global_load_dwordx2 v[52:53], v[138:139], off offset:48
	global_load_dwordx2 v[54:55], v[138:139], off offset:64
	global_load_dwordx2 v[56:57], v[138:139], off offset:80
	global_load_dwordx2 v[58:59], v[138:139], off offset:96
	global_load_dwordx2 v[60:61], v[138:139], off offset:112
	global_load_dwordx2 v[98:99], v[146:147], off
	global_load_dwordx2 v[100:101], v[146:147], off offset:16
	global_load_dwordx2 v[102:103], v[146:147], off offset:32
	global_load_dwordx2 v[104:105], v[146:147], off offset:48
	global_load_dwordx2 v[106:107], v[146:147], off offset:64
	global_load_dwordx2 v[108:109], v[146:147], off offset:80
	global_load_dwordx2 v[158:159], v[96:97], off
	v_mfma_f32_32x32x16_bf16 v[16:31], v[24:27], v[80:83], 0
	global_load_dwordx2 v[110:111], v[146:147], off offset:96
	global_load_dwordx2 v[112:113], v[146:147], off offset:112
	global_load_dwordx2 v[114:115], v[48:49], off offset:128
	global_load_dwordx2 v[116:117], v[48:49], off offset:144
	global_load_dwordx2 v[118:119], v[48:49], off offset:160
	global_load_dwordx2 v[120:121], v[48:49], off offset:176
	global_load_dwordx2 v[122:123], v[48:49], off offset:192
	global_load_dwordx2 v[124:125], v[48:49], off offset:208
	global_load_dwordx2 v[126:127], v[48:49], off offset:224
	global_load_dwordx2 v[128:129], v[48:49], off offset:240
	global_load_dwordx2 v[130:131], v[138:139], off offset:128
	global_load_dwordx2 v[132:133], v[138:139], off offset:144
	global_load_dwordx2 v[134:135], v[138:139], off offset:160
	global_load_dwordx2 v[136:137], v[138:139], off offset:176
	v_mfma_f32_32x32x16_bf16 v[16:31], v[36:39], v[84:87], v[16:31]
	v_mfma_f32_32x32x16_bf16 v[16:31], v[40:43], v[88:91], v[16:31]
	v_mfma_f32_32x32x16_bf16 v[16:31], v[44:47], v[92:95], v[16:31]
	s_waitcnt vmcnt(0)
	v_mfma_f32_32x32x16_bf16 v[32:47], v[32:35], v[80:83], 0
	v_mfma_f32_32x32x16_bf16 v[32:47], v[50:53], v[84:87], v[32:47]
	v_mfma_f32_32x32x16_bf16 v[32:47], v[54:57], v[88:91], v[32:47]
	v_mfma_f32_32x32x16_bf16 v[32:47], v[58:61], v[92:95], v[32:47]
	v_mfma_f32_32x32x16_bf16 v[48:63], v[98:101], v[80:83], 0
	global_load_dwordx2 v[80:81], v[138:139], off offset:192
	global_load_dwordx2 v[82:83], v[138:139], off offset:208
	global_load_dwordx2 v[98:99], v[138:139], off offset:224
	global_load_dwordx2 v[100:101], v[138:139], off offset:240
	s_nop 0
	global_load_dwordx2 v[138:139], v[146:147], off offset:128
	global_load_dwordx2 v[140:141], v[146:147], off offset:144
	global_load_dwordx2 v[142:143], v[146:147], off offset:160
	global_load_dwordx2 v[144:145], v[146:147], off offset:176
	v_mfma_f32_32x32x16_bf16 v[48:63], v[102:105], v[84:87], v[48:63]
	global_load_dwordx2 v[84:85], v[146:147], off offset:192
	global_load_dwordx2 v[86:87], v[146:147], off offset:208
	global_load_dwordx2 v[102:103], v[146:147], off offset:224
	global_load_dwordx2 v[104:105], v[146:147], off offset:240
	v_lshlrev_b32_e32 v146, 16, v158
	v_and_b32_e32 v147, 0xffff0000, v158
	v_lshlrev_b32_e32 v158, 16, v159
	v_mul_f32_e32 v0, v0, v146
	v_mul_f32_e32 v1, v1, v147
	v_cvt_pk_bf16_f32 v0, v0, v1
	v_mfma_f32_32x32x16_bf16 v[48:63], v[106:109], v[88:91], v[48:63]
	v_and_b32_e32 v88, 0xffff0000, v159
	v_mul_f32_e32 v1, v2, v158
	v_mul_f32_e32 v2, v3, v88
	v_cvt_pk_bf16_f32 v1, v1, v2
	s_nop 0
	global_store_dwordx2 v[96:97], v[0:1], off
	v_mfma_f32_32x32x16_bf16 v[16:31], v[114:117], v[76:79], v[16:31]
	s_waitcnt vmcnt(1)
	v_lshlrev_b32_e32 v0, 16, v208
	v_and_b32_e32 v1, 0xffff0000, v208
	v_lshlrev_b32_e32 v2, 16, v209
	v_and_b32_e32 v3, 0xffff0000, v209
	v_mul_f32_e32 v0, v4, v0
	v_mul_f32_e32 v1, v5, v1
	v_mul_f32_e32 v2, v6, v2
	v_mul_f32_e32 v3, v7, v3
	v_cvt_pk_bf16_f32 v0, v0, v1
	v_cvt_pk_bf16_f32 v1, v2, v3
	v_mfma_f32_32x32x16_bf16 v[16:31], v[118:121], v[72:75], v[16:31]
	global_store_dwordx2 v[96:97], v[0:1], off offset:16
	v_lshlrev_b32_e32 v0, 16, v210
	v_and_b32_e32 v1, 0xffff0000, v210
	v_lshlrev_b32_e32 v2, 16, v211
	v_and_b32_e32 v3, 0xffff0000, v211
	v_mul_f32_e32 v0, v8, v0
	v_mul_f32_e32 v1, v9, v1
	v_mul_f32_e32 v2, v10, v2
	v_mul_f32_e32 v3, v11, v3
	v_cvt_pk_bf16_f32 v0, v0, v1
	v_cvt_pk_bf16_f32 v1, v2, v3
	v_mfma_f32_32x32x16_bf16 v[16:31], v[122:125], v[68:71], v[16:31]
	global_store_dwordx2 v[96:97], v[0:1], off offset:32
	v_lshlrev_b32_e32 v0, 16, v212
	v_and_b32_e32 v1, 0xffff0000, v212
	v_lshlrev_b32_e32 v2, 16, v213
	v_and_b32_e32 v3, 0xffff0000, v213
	v_mul_f32_e32 v0, v12, v0
	v_mul_f32_e32 v1, v13, v1
	v_mul_f32_e32 v2, v14, v2
	v_mul_f32_e32 v3, v15, v3
	v_cvt_pk_bf16_f32 v0, v0, v1
	v_cvt_pk_bf16_f32 v1, v2, v3
	v_mfma_f32_32x32x16_bf16 v[16:31], v[126:129], v[64:67], v[16:31]
	global_store_dwordx2 v[96:97], v[0:1], off offset:48
	v_lshlrev_b32_e32 v0, 16, v214
	v_and_b32_e32 v1, 0xffff0000, v214
	v_lshlrev_b32_e32 v2, 16, v215
	v_and_b32_e32 v3, 0xffff0000, v215
	s_nop 5
	v_mul_f32_e32 v0, v16, v0
	v_mul_f32_e32 v1, v17, v1
	v_mul_f32_e32 v2, v18, v2
	v_mul_f32_e32 v3, v19, v3
	v_cvt_pk_bf16_f32 v0, v0, v1
	v_cvt_pk_bf16_f32 v1, v2, v3
	v_mfma_f32_32x32x16_bf16 v[32:47], v[130:133], v[76:79], v[32:47]
	global_store_dwordx2 v[96:97], v[0:1], off offset:64
	v_lshlrev_b32_e32 v0, 16, v216
	v_and_b32_e32 v1, 0xffff0000, v216
	v_lshlrev_b32_e32 v2, 16, v217
	v_and_b32_e32 v3, 0xffff0000, v217
	v_mul_f32_e32 v0, v20, v0
	v_mul_f32_e32 v1, v21, v1
	v_mul_f32_e32 v2, v22, v2
	v_mul_f32_e32 v3, v23, v3
	v_cvt_pk_bf16_f32 v0, v0, v1
	v_cvt_pk_bf16_f32 v1, v2, v3
	v_mfma_f32_32x32x16_bf16 v[32:47], v[134:137], v[72:75], v[32:47]
	global_store_dwordx2 v[96:97], v[0:1], off offset:80
	v_lshlrev_b32_e32 v0, 16, v218
	v_and_b32_e32 v1, 0xffff0000, v218
	v_lshlrev_b32_e32 v2, 16, v219
	v_and_b32_e32 v3, 0xffff0000, v219
	v_mul_f32_e32 v0, v24, v0
	v_mul_f32_e32 v1, v25, v1
	v_mul_f32_e32 v2, v26, v2
	v_mul_f32_e32 v3, v27, v3
	v_cvt_pk_bf16_f32 v0, v0, v1
	v_cvt_pk_bf16_f32 v1, v2, v3
	v_mfma_f32_32x32x16_bf16 v[32:47], v[80:83], v[68:71], v[32:47]
	global_store_dwordx2 v[96:97], v[0:1], off offset:96
	v_lshlrev_b32_e32 v0, 16, v220
	v_and_b32_e32 v1, 0xffff0000, v220
	v_lshlrev_b32_e32 v2, 16, v221
	v_and_b32_e32 v3, 0xffff0000, v221
	v_mul_f32_e32 v0, v28, v0
	v_mul_f32_e32 v1, v29, v1
	v_mul_f32_e32 v2, v30, v2
	v_mul_f32_e32 v3, v31, v3
	v_cvt_pk_bf16_f32 v0, v0, v1
	v_cvt_pk_bf16_f32 v1, v2, v3
	v_mfma_f32_32x32x16_bf16 v[32:47], v[98:101], v[64:67], v[32:47]
	global_store_dwordx2 v[96:97], v[0:1], off offset:112
	v_lshlrev_b32_e32 v0, 16, v222
	v_and_b32_e32 v1, 0xffff0000, v222
	v_lshlrev_b32_e32 v2, 16, v223
	v_and_b32_e32 v3, 0xffff0000, v223
	s_nop 5
	v_mul_f32_e32 v0, v32, v0
	v_mul_f32_e32 v1, v33, v1
	v_mul_f32_e32 v2, v34, v2
	v_mul_f32_e32 v3, v35, v3
	v_cvt_pk_bf16_f32 v0, v0, v1
	v_cvt_pk_bf16_f32 v1, v2, v3
	v_mfma_f32_32x32x16_bf16 v[48:63], v[110:113], v[92:95], v[48:63]
	global_store_dwordx2 v[96:97], v[0:1], off offset:128
	v_lshlrev_b32_e32 v0, 16, v224
	v_and_b32_e32 v1, 0xffff0000, v224
	v_lshlrev_b32_e32 v2, 16, v225
	v_and_b32_e32 v3, 0xffff0000, v225
	v_mul_f32_e32 v0, v36, v0
	v_mul_f32_e32 v1, v37, v1
	v_mul_f32_e32 v2, v38, v2
	v_mul_f32_e32 v3, v39, v3
	v_cvt_pk_bf16_f32 v0, v0, v1
	v_cvt_pk_bf16_f32 v1, v2, v3
	v_mfma_f32_32x32x16_bf16 v[48:63], v[138:141], v[76:79], v[48:63]
	global_store_dwordx2 v[96:97], v[0:1], off offset:144
	v_lshlrev_b32_e32 v0, 16, v226
	v_and_b32_e32 v1, 0xffff0000, v226
	v_lshlrev_b32_e32 v2, 16, v227
	v_and_b32_e32 v3, 0xffff0000, v227
	v_mul_f32_e32 v0, v40, v0
	v_mul_f32_e32 v1, v41, v1
	v_mul_f32_e32 v2, v42, v2
	v_mul_f32_e32 v3, v43, v3
	v_cvt_pk_bf16_f32 v0, v0, v1
	v_cvt_pk_bf16_f32 v1, v2, v3
	v_mfma_f32_32x32x16_bf16 v[48:63], v[142:145], v[72:75], v[48:63]
	global_store_dwordx2 v[96:97], v[0:1], off offset:160
	v_lshlrev_b32_e32 v0, 16, v228
	v_and_b32_e32 v1, 0xffff0000, v228
	v_lshlrev_b32_e32 v2, 16, v229
	v_and_b32_e32 v3, 0xffff0000, v229
	v_mul_f32_e32 v0, v44, v0
	v_mul_f32_e32 v1, v45, v1
	v_mul_f32_e32 v2, v46, v2
	v_mul_f32_e32 v3, v47, v3
	v_cvt_pk_bf16_f32 v0, v0, v1
	v_cvt_pk_bf16_f32 v1, v2, v3
	v_mfma_f32_32x32x16_bf16 v[48:63], v[84:87], v[68:71], v[48:63]
	global_store_dwordx2 v[96:97], v[0:1], off offset:176
	v_lshlrev_b32_e32 v0, 16, v230
	v_mfma_f32_32x32x16_bf16 v[48:63], v[102:105], v[64:67], v[48:63]
	v_and_b32_e32 v1, 0xffff0000, v230
	v_lshlrev_b32_e32 v2, 16, v231
	v_and_b32_e32 v3, 0xffff0000, v231
	s_nop 8
	v_mul_f32_e32 v0, v48, v0
	v_mul_f32_e32 v1, v49, v1
	v_mul_f32_e32 v2, v50, v2
	v_mul_f32_e32 v3, v51, v3
	v_cvt_pk_bf16_f32 v0, v0, v1
	v_cvt_pk_bf16_f32 v1, v2, v3
	s_nop 0
	global_store_dwordx2 v[96:97], v[0:1], off offset:192
	v_lshlrev_b32_e32 v0, 16, v232
	v_and_b32_e32 v1, 0xffff0000, v232
	v_lshlrev_b32_e32 v2, 16, v233
	v_and_b32_e32 v3, 0xffff0000, v233
	v_mul_f32_e32 v0, v52, v0
	v_mul_f32_e32 v1, v53, v1
	v_mul_f32_e32 v2, v54, v2
	v_mul_f32_e32 v3, v55, v3
	v_cvt_pk_bf16_f32 v0, v0, v1
	v_cvt_pk_bf16_f32 v1, v2, v3
	s_nop 0
	global_store_dwordx2 v[96:97], v[0:1], off offset:208
	v_lshlrev_b32_e32 v0, 16, v234
	v_and_b32_e32 v1, 0xffff0000, v234
	v_lshlrev_b32_e32 v2, 16, v235
	v_and_b32_e32 v3, 0xffff0000, v235
	v_mul_f32_e32 v0, v56, v0
	v_mul_f32_e32 v1, v57, v1
	v_mul_f32_e32 v2, v58, v2
	v_mul_f32_e32 v3, v59, v3
	v_cvt_pk_bf16_f32 v0, v0, v1
	v_cvt_pk_bf16_f32 v1, v2, v3
	s_nop 0
	global_store_dwordx2 v[96:97], v[0:1], off offset:224
	v_lshlrev_b32_e32 v0, 16, v236
	v_and_b32_e32 v1, 0xffff0000, v236
	v_lshlrev_b32_e32 v2, 16, v237
	v_and_b32_e32 v3, 0xffff0000, v237
	v_mul_f32_e32 v0, v60, v0
	v_mul_f32_e32 v1, v61, v1
	v_mul_f32_e32 v2, v62, v2
	v_mul_f32_e32 v3, v63, v3
	v_cvt_pk_bf16_f32 v0, v0, v1
	v_cvt_pk_bf16_f32 v1, v2, v3
	global_store_dwordx2 v[96:97], v[0:1], off offset:240
	s_waitcnt lgkmcnt(0)
	s_barrier
	s_cbranch_scc1 .LBB0_525

.LBB0_519:
	s_lshl_b64 s[98:99], s[14:15], 12
	s_add_u32 s98, s23, s98
	s_addc_u32 s99, s24, s99
	s_lshl_b32 s100, s0, 8
	s_add_u32 s98, s98, s100
	s_addc_u32 s99, s99, 0
	v_lshl_add_u64 v[208:209], s[98:99], 0, v[154:155]
	v_lshl_add_u64 v[208:209], v[208:209], 0, v[150:151]
	global_load_dwordx2 v[210:211], v[208:209], off offset:32
	global_load_dwordx2 v[212:213], v[208:209], off offset:48
	global_load_dwordx2 v[214:215], v[208:209], off offset:64
	global_load_dwordx2 v[216:217], v[208:209], off offset:80
	global_load_dwordx2 v[218:219], v[208:209], off offset:96
	global_load_dwordx2 v[220:221], v[208:209], off offset:112
	global_load_dwordx2 v[222:223], v[208:209], off offset:128
	global_load_dwordx2 v[224:225], v[208:209], off offset:144
	global_load_dwordx2 v[226:227], v[208:209], off offset:160
	global_load_dwordx2 v[228:229], v[208:209], off offset:176
	global_load_dwordx2 v[230:231], v[208:209], off offset:192
	global_load_dwordx2 v[232:233], v[208:209], off offset:208
	global_load_dwordx2 v[234:235], v[208:209], off offset:224
	global_load_dwordx2 v[236:237], v[208:209], off offset:240
	global_load_dwordx2 v[208:209], v[208:209], off offset:16
	s_nop 4
	v_max_f32_e32 v96, v81, v81
	v_max_f32_e32 v97, v80, v80
	v_max_f32_e32 v96, v97, v96
	v_max3_f32 v96, v96, v82, v83
	v_max3_f32 v96, v96, v84, v85
	v_max3_f32 v96, v96, v86, v87
	v_max3_f32 v96, v96, v88, v89
	v_max3_f32 v96, v96, v90, v91
	v_max3_f32 v96, v96, v92, v93
	v_max3_f32 v96, v96, v94, v95
	v_max3_f32 v96, v96, v64, v65
	v_max3_f32 v96, v96, v66, v67
	v_max3_f32 v96, v96, v68, v69
	v_max3_f32 v96, v96, v70, v71
	v_max3_f32 v96, v96, v72, v73
	v_max3_f32 v96, v96, v74, v75
	v_max3_f32 v96, v96, v76, v77
	v_max3_f32 v96, v96, v78, v79
	v_mov_b32_e32 v97, v96
	s_nop 1
	v_permlane32_swap_b32_e32 v96, v97
	v_max_f32_e32 v97, v97, v97
	v_max_f32_e32 v96, v96, v96
	v_max_f32_e32 v97, v96, v97
	v_cmp_ge_f32_e32 vcc, s39, v97
	s_cmp_eq_u64 vcc, exec
	v_mov_b32_e32 v96, 1.0
	s_cbranch_scc0 .LBB0_524
	v_cmp_gt_f32_e32 vcc, 1.0, v96
	s_cbranch_vccz .LBB0_522

	.amdhsa_kernel _Z10fwd_kernel6Params
		.amdhsa_group_segment_fixed_size 0
		.amdhsa_private_segment_fixed_size 0
		.amdhsa_kernarg_size 440
		.amdhsa_user_sgpr_count 2
		.amdhsa_user_sgpr_dispatch_ptr 0
		.amdhsa_user_sgpr_queue_ptr 0
		.amdhsa_user_sgpr_kernarg_segment_ptr 1
		.amdhsa_user_sgpr_dispatch_id 0
		.amdhsa_user_sgpr_kernarg_preload_length 0
		.amdhsa_user_sgpr_kernarg_preload_offset 0
		.amdhsa_user_sgpr_private_segment_size 0
		.amdhsa_uses_dynamic_stack 0
		.amdhsa_enable_private_segment 0
		.amdhsa_system_sgpr_workgroup_id_x 1
		.amdhsa_system_sgpr_workgroup_id_y 0
		.amdhsa_system_sgpr_workgroup_id_z 0
		.amdhsa_system_sgpr_workgroup_info 0
		.amdhsa_system_vgpr_workitem_id 2
		.amdhsa_next_free_vgpr 256
		.amdhsa_next_free_sgpr 101
		.amdhsa_accum_offset 256
		.amdhsa_reserve_vcc 1
		.amdhsa_float_round_mode_32 0
		.amdhsa_float_round_mode_16_64 0
		.amdhsa_float_denorm_mode_32 3
		.amdhsa_float_denorm_mode_16_64 3
		.amdhsa_dx10_clamp 1
		.amdhsa_ieee_mode 1
		.amdhsa_fp16_overflow 0
		.amdhsa_tg_split 0
		.amdhsa_exception_fp_ieee_invalid_op 0
		.amdhsa_exception_fp_denorm_src 0
		.amdhsa_exception_fp_ieee_div_zero 0
		.amdhsa_exception_fp_ieee_overflow 0
		.amdhsa_exception_fp_ieee_underflow 0
		.amdhsa_exception_fp_ieee_inexact 0
		.amdhsa_exception_int_div_zero 0
	.end_amdhsa_kernel

amdhsa.kernels:
  - .agpr_count:     0
    .args:
      - .offset:         0
        .size:           184
        .value_kind:     by_value
      - .offset:         184
        .size:           4
        .value_kind:     hidden_block_count_x
      - .offset:         188
        .size:           4
        .value_kind:     hidden_block_count_y
      - .offset:         192
        .size:           4
        .value_kind:     hidden_block_count_z
      - .offset:         196
        .size:           2
        .value_kind:     hidden_group_size_x
      - .offset:         198
        .size:           2
        .value_kind:     hidden_group_size_y
      - .offset:         200
        .size:           2
        .value_kind:     hidden_group_size_z
      - .offset:         202
        .size:           2
        .value_kind:     hidden_remainder_x
      - .offset:         204
        .size:           2
        .value_kind:     hidden_remainder_y
      - .offset:         206
        .size:           2
        .value_kind:     hidden_remainder_z
      - .offset:         224
        .size:           8
        .value_kind:     hidden_global_offset_x
      - .offset:         232
        .size:           8
        .value_kind:     hidden_global_offset_y
      - .offset:         240
        .size:           8
        .value_kind:     hidden_global_offset_z
      - .offset:         248
        .size:           2
        .value_kind:     hidden_grid_dims
      - .offset:         272
        .size:           8
        .value_kind:     hidden_multigrid_sync_arg
      - .offset:         304
        .size:           4
        .value_kind:     hidden_dynamic_lds_size
    .group_segment_fixed_size: 0
    .kernarg_segment_align: 8
    .kernarg_segment_size: 440
    .language:       OpenCL C
    .language_version:
      - 2
      - 0
    .max_flat_workgroup_size: 512
    .name:           _Z10fwd_kernel6Params
    .private_segment_fixed_size: 0
    .sgpr_count:     107
    .sgpr_spill_count: 37
    .symbol:         _Z10fwd_kernel6Params.kd
    .uniform_work_group_size: 1
    .uses_dynamic_stack: false
    .vgpr_count:     256
    .vgpr_spill_count: 0
    .wavefront_size: 64
